# T3 + odd-layer attention loops issue next-tile global loads after the LDS fragment reads (LDS reads start earlier each iteration)
# baseline (speedup 1.0000x reference)
; template <int DK, int MODE, bool OUTF32> ...
;     ...
;     for (int t = t_lo; t < t_hi; ++t) {
;         const int cur = (t - t_lo) & 1;
;         if (t + 1 < t_hi) A_ISSUE(t + 1);
;         bool act;
;         if (MODE == 0) act = (64 * t + 32 * kh) <= (qw0 + 31);
;         else if (MODE == 1) act = (t <= cw) && (t >= cw - 8);
;         else act = (t <= cw);
;         if (act) {
;             f32x16 p;
; #pragma unroll
;             for (int r = 0; r < 16; ++r) p[r] = 0.f;
;             const unsigned char* kb = a_lds + cur * KBUF + (32 * kh + c) * KP + hi * 16;
;             constexpr bool HOISTK = true;
;             bf16x8 kf[NKS];
;             if (HOISTK) {
; #pragma unroll
;                 for (int s = 0; s < NKS; ++s) kf[s] = *(const bf16x8*)(kb + s * 32);
;             }
;             const unsigned char* vb = a_lds + OFF_V + cur * VBUF + c * VP + (32 * kh + 4 * hi) * 2;
;             bf16x8 vf[8];
;     ...
;             constexpr bool HOISTV = (DK == 128) && (MODE == 2 || MODE == 1);
;             if (HOISTV) A_VREADS(0, 3);
;             if (HOISTK) __builtin_amdgcn_sched_barrier(0);
; #pragma unroll
;             for (int s = 0; s < NKS; ++s) p = __builtin_amdgcn_mfma_f32_32x32x16_bf16(HOISTK ? kf[s] : *(const bf16x8*)(kb + s * 32), qf[s], p, 0, 0, 0);
;             if (HOISTV) { A_VREADS(3, 4); __builtin_amdgcn_sched_barrier(0); }
;             if (MODE == 0) {
;                 const float* ckp = (const float*)(a_lds + OFF_CK + cur * 256) + 32 * kh + 4 * hi;
; #pragma unroll
;                 for (int g = 0; g < 4; ++g) {
;                     const float4 ck = *(const float4*)(ckp + 8 * g);
;                     p[4 * g + 0] = fmaf(p[4 * g + 0], sc2, cq - ck.x); p[4 * g + 1] = fmaf(p[4 * g + 1], sc2, cq - ck.y);
;                     p[4 * g + 2] = fmaf(p[4 * g + 2], sc2, cq - ck.z); p[4 * g + 3] = fmaf(p[4 * g + 3], sc2, cq - ck.w);
;                 }
;                 if (64 * t + 32 * kh + 31 > qw0) {
;                     const int kbase = 64 * t + 32 * kh + 4 * hi;
; #pragma unroll
;                     for (int r = 0; r < 16; ++r) if (kbase + (r & 3) + 8 * (r >> 2) > qrow) p[r] = NEGINF;
;                 }
;             } else if (MODE == 1) {
;                 const float* rb = (const float*)(a_lds + OFF_RB);
;                 if (t <= cw - 3) {
;                     const float bb = rb[256];
; #pragma unroll
.LBB0_943:
	s_and_b32 s13, s12, 1
	v_cmp_le_i32_e32 vcc, s12, v187
	s_and_saveexec_b64 s[50:51], vcc
	s_cbranch_execz .Ldiff_inact
	s_mul_i32 s14, s13, 0x4400
	v_add_u32_e32 v72, s14, v183
	ds_read_b128 v[68:71], v72
	ds_read_b128 v[156:159], v72 offset:32
	ds_read_b128 v[160:163], v72 offset:64
	ds_read_b128 v[192:195], v72 offset:96
	ds_read_b128 v[208:211], v72 offset:128
	ds_read_b128 v[212:215], v72 offset:160
	ds_read_b128 v[216:219], v72 offset:192
	ds_read_b128 v[220:223], v72 offset:224
	v_add_u32_e32 v196, s14, v184
	v_add_u32_e32 v72, 0xc800, v196
	ds_read2_b64 v[132:135], v72 offset1:2
	ds_read2_b64 v[136:139], v72 offset0:4 offset1:6
	v_add_u32_e32 v72, 0xd800, v196
	ds_read2_b64 v[140:143], v72 offset0:32 offset1:34
	ds_read2_b64 v[144:147], v72 offset0:36 offset1:38
	v_add_u32_e32 v72, 0xe800, v196
	ds_read2_b64 v[148:151], v72 offset0:64 offset1:66
	ds_read2_b64 v[152:155], v72 offset0:68 offset1:70
	v_add_co_u32_e32 v240, vcc, 0xfff80000, v172
	global_load_dwordx4 v[120:123], v[174:175], off
	global_load_dwordx4 v[116:119], v[176:177], off
	v_addc_co_u32_e32 v241, vcc, -1, v173, vcc
	global_load_dwordx4 v[128:131], v[240:241], off
	global_load_dwordx4 v[124:127], v[172:173], off
	s_waitcnt lgkmcnt(13)
	v_mfma_f32_32x32x16_bf16 v[68:83], v[68:71], v[112:115], 0
	s_waitcnt lgkmcnt(12)
	v_mfma_f32_32x32x16_bf16 v[68:83], v[156:159], v[108:111], v[68:83]
	v_add_u32_e32 v156, 0xf800, v196
	s_waitcnt lgkmcnt(11)
	v_mfma_f32_32x32x16_bf16 v[68:83], v[160:163], v[104:107], v[68:83]
	ds_read2_b64 v[160:163], v156 offset0:96 offset1:98
	ds_read2_b64 v[156:159], v156 offset0:100 offset1:102
	s_waitcnt lgkmcnt(12)
	v_mfma_f32_32x32x16_bf16 v[68:83], v[192:195], v[100:103], v[68:83]
	s_waitcnt lgkmcnt(11)
	v_mfma_f32_32x32x16_bf16 v[68:83], v[208:211], v[96:99], v[68:83]
	s_waitcnt lgkmcnt(10)
	v_mfma_f32_32x32x16_bf16 v[68:83], v[212:215], v[92:95], v[68:83]
	s_waitcnt lgkmcnt(9)
	v_mfma_f32_32x32x16_bf16 v[68:83], v[216:219], v[88:91], v[68:83]
	s_waitcnt lgkmcnt(8)
	v_mfma_f32_32x32x16_bf16 v[68:83], v[220:223], v[84:87], v[68:83]
	s_nop 11
	v_max_f32_e32 v192, v69, v69
	v_max_f32_e32 v193, v68, v68
	v_max_f32_e32 v192, v193, v192
	v_max3_f32 v192, v192, v70, v71
	v_max3_f32 v192, v192, v72, v73
	v_max3_f32 v192, v192, v74, v75
	v_max3_f32 v192, v192, v76, v77
	v_max3_f32 v192, v192, v78, v79
	v_max3_f32 v192, v192, v80, v81
	v_max3_f32 v192, v192, v82, v83
	v_mul_f32_e32 v192, 0x3e0293ee, v192
	v_mov_b32_e32 v193, v192
	s_nop 1
	v_permlane32_swap_b32_e32 v192, v193
	v_max_f32_e32 v193, v193, v193
	v_max_f32_e32 v192, v192, v192
	v_max_f32_e32 v192, v192, v193
	v_sub_f32_e32 v193, v192, v181
	s_mov_b32 s14, 0x41000000
	v_cmp_ge_f32_e32 vcc, s14, v193
	s_cmp_eq_u64 vcc, exec
	s_cbranch_scc1 .LBB0_941
	v_max_f32_e32 v192, v192, v192
	v_max_f32_e32 v193, v181, v181
	v_max_f32_e32 v193, v193, v192
	v_sub_f32_e32 v181, v181, v193
	v_exp_f32_e32 v192, v181
	v_mov_b32_e32 v181, v193
	v_pk_mul_f32 v[66:67], v[66:67], v[192:193] op_sel_hi:[1,0]
	v_pk_mul_f32 v[64:65], v[64:65], v[192:193] op_sel_hi:[1,0]
	v_pk_mul_f32 v[62:63], v[62:63], v[192:193] op_sel_hi:[1,0]
	v_pk_mul_f32 v[60:61], v[60:61], v[192:193] op_sel_hi:[1,0]
	v_pk_mul_f32 v[58:59], v[58:59], v[192:193] op_sel_hi:[1,0]
	v_pk_mul_f32 v[56:57], v[56:57], v[192:193] op_sel_hi:[1,0]
	v_pk_mul_f32 v[54:55], v[54:55], v[192:193] op_sel_hi:[1,0]
	v_pk_mul_f32 v[52:53], v[52:53], v[192:193] op_sel_hi:[1,0]
	v_pk_mul_f32 v[34:35], v[34:35], v[192:193] op_sel_hi:[1,0]
	v_pk_mul_f32 v[32:33], v[32:33], v[192:193] op_sel_hi:[1,0]
	v_pk_mul_f32 v[30:31], v[30:31], v[192:193] op_sel_hi:[1,0]
	v_pk_mul_f32 v[28:29], v[28:29], v[192:193] op_sel_hi:[1,0]
	v_pk_mul_f32 v[26:27], v[26:27], v[192:193] op_sel_hi:[1,0]
	v_pk_mul_f32 v[24:25], v[24:25], v[192:193] op_sel_hi:[1,0]
	v_pk_mul_f32 v[22:23], v[22:23], v[192:193] op_sel_hi:[1,0]
	v_pk_mul_f32 v[20:21], v[20:21], v[192:193] op_sel_hi:[1,0]
	v_pk_mul_f32 v[50:51], v[50:51], v[192:193] op_sel_hi:[1,0]
	v_pk_mul_f32 v[48:49], v[48:49], v[192:193] op_sel_hi:[1,0]
	v_pk_mul_f32 v[46:47], v[46:47], v[192:193] op_sel_hi:[1,0]
	v_pk_mul_f32 v[44:45], v[44:45], v[192:193] op_sel_hi:[1,0]
	v_pk_mul_f32 v[42:43], v[42:43], v[192:193] op_sel_hi:[1,0]
	v_pk_mul_f32 v[40:41], v[40:41], v[192:193] op_sel_hi:[1,0]
	v_pk_mul_f32 v[38:39], v[38:39], v[192:193] op_sel_hi:[1,0]
	v_pk_mul_f32 v[36:37], v[36:37], v[192:193] op_sel_hi:[1,0]
	v_pk_mul_f32 v[18:19], v[18:19], v[192:193] op_sel_hi:[1,0]
	v_pk_mul_f32 v[16:17], v[16:17], v[192:193] op_sel_hi:[1,0]
	v_pk_mul_f32 v[14:15], v[14:15], v[192:193] op_sel_hi:[1,0]
	v_pk_mul_f32 v[12:13], v[12:13], v[192:193] op_sel_hi:[1,0]
	v_pk_mul_f32 v[10:11], v[10:11], v[192:193] op_sel_hi:[1,0]
	v_pk_mul_f32 v[8:9], v[8:9], v[192:193] op_sel_hi:[1,0]
	v_pk_mul_f32 v[6:7], v[6:7], v[192:193] op_sel_hi:[1,0]
	v_pk_mul_f32 v[4:5], v[4:5], v[192:193] op_sel_hi:[1,0]
	v_mul_f32_e32 v179, v179, v192
	s_branch .LBB0_941
.Ldiff_inact:
	s_or_b64 exec, exec, s[50:51]
	v_add_co_u32_e32 v240, vcc, 0xfff80000, v172
	global_load_dwordx4 v[120:123], v[174:175], off
	global_load_dwordx4 v[116:119], v[176:177], off
	v_addc_co_u32_e32 v241, vcc, -1, v173, vcc
	global_load_dwordx4 v[128:131], v[240:241], off
	global_load_dwordx4 v[124:127], v[172:173], off
	s_branch .LBB0_942

; template <int DK, int MODE, bool OUTF32> ...
;     ...
;     for (int t = t_lo; t < t_hi; ++t) {
;         const int cur = (t - t_lo) & 1;
;         if (t + 1 < t_hi) A_ISSUE(t + 1);
;         bool act;
;         if (MODE == 0) act = (64 * t + 32 * kh) <= (qw0 + 31);
;         else if (MODE == 1) act = (t <= cw) && (t >= cw - 8);
;         else act = (t <= cw);
;         if (act) {
;             f32x16 p;
; #pragma unroll
;             for (int r = 0; r < 16; ++r) p[r] = 0.f;
;             const unsigned char* kb = a_lds + cur * KBUF + (32 * kh + c) * KP + hi * 16;
;             constexpr bool HOISTK = true;
;             bf16x8 kf[NKS];
;             if (HOISTK) {
; #pragma unroll
;                 for (int s = 0; s < NKS; ++s) kf[s] = *(const bf16x8*)(kb + s * 32);
;             }
;             const unsigned char* vb = a_lds + OFF_V + cur * VBUF + c * VP + (32 * kh + 4 * hi) * 2;
;             bf16x8 vf[8];
;     ...
;             constexpr bool HOISTV = (DK == 128) && (MODE == 2 || MODE == 1);
;             if (HOISTV) A_VREADS(0, 3);
;             if (HOISTK) __builtin_amdgcn_sched_barrier(0);
; #pragma unroll
;             for (int s = 0; s < NKS; ++s) p = __builtin_amdgcn_mfma_f32_32x32x16_bf16(HOISTK ? kf[s] : *(const bf16x8*)(kb + s * 32), qf[s], p, 0, 0, 0);
;             if (HOISTV) { A_VREADS(3, 4); __builtin_amdgcn_sched_barrier(0); }
;             if (MODE == 0) {
;                 const float* ckp = (const float*)(a_lds + OFF_CK + cur * 256) + 32 * kh + 4 * hi;
; #pragma unroll
;                 for (int g = 0; g < 4; ++g) {
;                     const float4 ck = *(const float4*)(ckp + 8 * g);
;                     p[4 * g + 0] = fmaf(p[4 * g + 0], sc2, cq - ck.x); p[4 * g + 1] = fmaf(p[4 * g + 1], sc2, cq - ck.y);
;                     p[4 * g + 2] = fmaf(p[4 * g + 2], sc2, cq - ck.z); p[4 * g + 3] = fmaf(p[4 * g + 3], sc2, cq - ck.w);
;                 }
;                 if (64 * t + 32 * kh + 31 > qw0) {
;                     const int kbase = 64 * t + 32 * kh + 4 * hi;
; #pragma unroll
;                     for (int r = 0; r < 16; ++r) if (kbase + (r & 3) + 8 * (r >> 2) > qrow) p[r] = NEGINF;
;                 }
;             } else if (MODE == 1) {
;                 const float* rb = (const float*)(a_lds + OFF_RB);
;                 if (t <= cw - 3) {
;                     const float bb = rb[256];
; #pragma unroll
.LBB0_959:
	s_and_b32 s13, s12, 1
	v_cmp_le_i32_e32 vcc, s12, v179
	s_and_saveexec_b64 s[50:51], vcc
	s_cbranch_execz .Lmla_inact
	s_mul_i32 s14, s13, 0x6400
	v_add_u32_e32 v2, s14, v176
	ds_read_b128 v[82:85], v2
	ds_read_b128 v[186:189], v2 offset:32
	ds_read_b128 v[190:193], v2 offset:64
	ds_read_b128 v[194:197], v2 offset:96
	ds_read_b128 v[208:211], v2 offset:128
	ds_read_b128 v[212:215], v2 offset:160
	ds_read_b128 v[216:219], v2 offset:192
	ds_read_b128 v[220:223], v2 offset:224
	ds_read_b128 v[224:227], v2 offset:256
	ds_read_b128 v[228:231], v2 offset:288
	ds_read_b128 v[232:235], v2 offset:320
	ds_read_b128 v[236:239], v2 offset:352
	v_add_co_u32_e32 v246, vcc, 0xfff80000, v162
	v_lshl_add_u64 v[240:241], v[158:159], 0, v[164:165]
	v_lshl_add_u64 v[242:243], v[158:159], 0, v[168:169]
	v_lshl_add_u64 v[244:245], v[158:159], 0, v[166:167]
	v_addc_co_u32_e32 v247, vcc, -1, v163, vcc
	global_load_dwordx4 v[12:15], v[240:241], off
	global_load_dwordx4 v[4:7], v[242:243], off
	global_load_dwordx4 v[8:11], v[244:245], off
	global_load_dwordx4 v[150:153], v[246:247], off
	global_load_dwordx4 v[146:149], v[162:163], off
	s_waitcnt lgkmcnt(11)
	v_mfma_f32_32x32x16_bf16 v[82:97], v[82:85], v[142:145], 0
	s_mov_b32 s14, 0x41000000
	s_waitcnt lgkmcnt(10)
	v_mfma_f32_32x32x16_bf16 v[82:97], v[186:189], v[138:141], v[82:97]
	s_waitcnt lgkmcnt(9)
	v_mfma_f32_32x32x16_bf16 v[82:97], v[190:193], v[134:137], v[82:97]
	s_waitcnt lgkmcnt(8)
	v_mfma_f32_32x32x16_bf16 v[82:97], v[194:197], v[130:133], v[82:97]
	s_waitcnt lgkmcnt(7)
	v_mfma_f32_32x32x16_bf16 v[82:97], v[208:211], v[126:129], v[82:97]
	s_waitcnt lgkmcnt(6)
	v_mfma_f32_32x32x16_bf16 v[82:97], v[212:215], v[122:125], v[82:97]
	s_waitcnt lgkmcnt(5)
	v_mfma_f32_32x32x16_bf16 v[82:97], v[216:219], v[118:121], v[82:97]
	s_waitcnt lgkmcnt(4)
	v_mfma_f32_32x32x16_bf16 v[82:97], v[220:223], v[114:117], v[82:97]
	s_waitcnt lgkmcnt(3)
	v_mfma_f32_32x32x16_bf16 v[82:97], v[224:227], v[110:113], v[82:97]
	s_waitcnt lgkmcnt(2)
	v_mfma_f32_32x32x16_bf16 v[82:97], v[228:231], v[106:109], v[82:97]
	s_waitcnt lgkmcnt(1)
	v_mfma_f32_32x32x16_bf16 v[82:97], v[232:235], v[102:105], v[82:97]
	s_waitcnt lgkmcnt(0)
	v_mfma_f32_32x32x16_bf16 v[82:97], v[236:239], v[98:101], v[82:97]
	s_nop 11
	v_max_f32_e32 v2, v83, v83
	v_max_f32_e32 v16, v82, v82
	v_max_f32_e32 v2, v16, v2
	v_max3_f32 v2, v2, v84, v85
	v_max3_f32 v2, v2, v86, v87
	v_max3_f32 v2, v2, v88, v89
	v_max3_f32 v2, v2, v90, v91
	v_max3_f32 v2, v2, v92, v93
	v_max3_f32 v2, v2, v94, v95
	v_max3_f32 v2, v2, v96, v97
	v_mul_f32_e32 v2, 0x3dd53b94, v2
	v_mov_b32_e32 v16, v2
	s_nop 1
	v_permlane32_swap_b32_e32 v2, v16
	v_max_f32_e32 v16, v16, v16
	v_max_f32_e32 v2, v2, v2
	v_max_f32_e32 v2, v2, v16
	v_sub_f32_e32 v16, v2, v173
	v_cmp_ge_f32_e32 vcc, s14, v16
	s_cmp_eq_u64 vcc, exec
	s_cbranch_scc1 .LBB0_957
	v_max_f32_e32 v2, v2, v2
	v_max_f32_e32 v16, v173, v173
	v_max_f32_e32 v16, v16, v2
	v_sub_f32_e32 v2, v173, v16
	v_exp_f32_e32 v2, v2
	v_mov_b32_e32 v173, v16
	v_pk_mul_f32 v[80:81], v[80:81], v[2:3] op_sel_hi:[1,0]
	v_pk_mul_f32 v[78:79], v[78:79], v[2:3] op_sel_hi:[1,0]
	v_pk_mul_f32 v[76:77], v[76:77], v[2:3] op_sel_hi:[1,0]
	v_pk_mul_f32 v[74:75], v[74:75], v[2:3] op_sel_hi:[1,0]
	v_pk_mul_f32 v[72:73], v[72:73], v[2:3] op_sel_hi:[1,0]
	v_pk_mul_f32 v[70:71], v[70:71], v[2:3] op_sel_hi:[1,0]
	v_pk_mul_f32 v[68:69], v[68:69], v[2:3] op_sel_hi:[1,0]
	v_pk_mul_f32 v[66:67], v[66:67], v[2:3] op_sel_hi:[1,0]
	v_pk_mul_f32 v[48:49], v[48:49], v[2:3] op_sel_hi:[1,0]
	v_pk_mul_f32 v[46:47], v[46:47], v[2:3] op_sel_hi:[1,0]
	v_pk_mul_f32 v[44:45], v[44:45], v[2:3] op_sel_hi:[1,0]
	v_pk_mul_f32 v[42:43], v[42:43], v[2:3] op_sel_hi:[1,0]
	v_pk_mul_f32 v[40:41], v[40:41], v[2:3] op_sel_hi:[1,0]
	v_pk_mul_f32 v[38:39], v[38:39], v[2:3] op_sel_hi:[1,0]
	v_pk_mul_f32 v[36:37], v[36:37], v[2:3] op_sel_hi:[1,0]
	v_pk_mul_f32 v[34:35], v[34:35], v[2:3] op_sel_hi:[1,0]
	v_pk_mul_f32 v[64:65], v[64:65], v[2:3] op_sel_hi:[1,0]
	v_pk_mul_f32 v[62:63], v[62:63], v[2:3] op_sel_hi:[1,0]
	v_pk_mul_f32 v[60:61], v[60:61], v[2:3] op_sel_hi:[1,0]
	v_pk_mul_f32 v[58:59], v[58:59], v[2:3] op_sel_hi:[1,0]
	v_pk_mul_f32 v[56:57], v[56:57], v[2:3] op_sel_hi:[1,0]
	v_pk_mul_f32 v[54:55], v[54:55], v[2:3] op_sel_hi:[1,0]
	v_pk_mul_f32 v[52:53], v[52:53], v[2:3] op_sel_hi:[1,0]
	v_pk_mul_f32 v[50:51], v[50:51], v[2:3] op_sel_hi:[1,0]
	v_pk_mul_f32 v[32:33], v[32:33], v[2:3] op_sel_hi:[1,0]
	v_pk_mul_f32 v[30:31], v[30:31], v[2:3] op_sel_hi:[1,0]
	v_pk_mul_f32 v[28:29], v[28:29], v[2:3] op_sel_hi:[1,0]
	v_pk_mul_f32 v[26:27], v[26:27], v[2:3] op_sel_hi:[1,0]
	v_pk_mul_f32 v[24:25], v[24:25], v[2:3] op_sel_hi:[1,0]
	v_pk_mul_f32 v[22:23], v[22:23], v[2:3] op_sel_hi:[1,0]
	v_pk_mul_f32 v[20:21], v[20:21], v[2:3] op_sel_hi:[1,0]
	v_pk_mul_f32 v[18:19], v[18:19], v[2:3] op_sel_hi:[1,0]
	v_mul_f32_e32 v171, v171, v2
	s_branch .LBB0_957
.Lmla_inact:
	s_or_b64 exec, exec, s[50:51]
	v_add_co_u32_e32 v246, vcc, 0xfff80000, v162
	v_lshl_add_u64 v[240:241], v[158:159], 0, v[164:165]
	v_lshl_add_u64 v[242:243], v[158:159], 0, v[168:169]
	v_lshl_add_u64 v[244:245], v[158:159], 0, v[166:167]
	v_addc_co_u32_e32 v247, vcc, -1, v163, vcc
	global_load_dwordx4 v[12:15], v[240:241], off
	global_load_dwordx4 v[4:7], v[242:243], off
	global_load_dwordx4 v[8:11], v[244:245], off
	global_load_dwordx4 v[150:153], v[246:247], off
	global_load_dwordx4 v[146:149], v[162:163], off
	s_branch .LBB0_958
